# K-order cross-phase overlap: last 112 FFN-in tiles of the 3 conversion-free FFNs run on the 96 idle WGs during FFN-out, per-M-tile flags
# speedup vs baseline: 1.0173x; 1.0173x over previous
.LBB0_263:
	v_writelane_b32 v253, s63, 9
	s_or_b64 exec, exec, s[6:7]
	s_cmpk_lt_i32 s2, 0xc8
	s_cselect_b64 s[4:5], -1, 0
	v_writelane_b32 v253, s4, 10
	s_mul_i32 s34, s67, s66
	s_mul_i32 s34, s34, s68
	v_writelane_b32 v253, s5, 11
	s_lshr_b32 s4, s3, 29
	s_add_i32 s4, s2, s4
	s_ashr_i32 s5, s4, 3
	s_and_b32 s4, s4, -8
	s_sub_i32 s7, s2, s4
	s_cmpk_lt_i32 s2, 0xf0
	s_cselect_b64 s[8:9], -1, 0
	v_writelane_b32 v253, s8, 12
	s_cmpk_lt_i32 s2, 0x150
	s_movk_i32 s81, 0x1080
	v_writelane_b32 v253, s9, 13
	s_cselect_b64 s[8:9], -1, 0
	s_cmpk_gt_i32 s2, 0x7f
	s_cselect_b64 s[56:57], -1, 0
	s_lshl_b32 s4, s2, 2
	s_add_i32 s77, s4, 0xfffffe80
	v_writelane_b32 v253, s8, 14
	s_cmpk_lt_i32 s2, 0xa0
	v_mov_b32_e32 v227, 0x358637bd
	v_writelane_b32 v253, s9, 15
	s_cselect_b64 s[8:9], -1, 0
	v_writelane_b32 v253, s8, 16
	s_cmpk_gt_i32 s2, 0x9f
	v_mov_b32_e32 v252, 1
	v_writelane_b32 v253, s9, 17
	s_cselect_b64 s[8:9], -1, 0
	v_writelane_b32 v253, s8, 18
	v_mbcnt_hi_u32_b32 v232, -1, v88
	v_mov_b32_e32 v233, 0x600
	v_writelane_b32 v253, s9, 19
	v_mov_b32_e32 v178, 0xf149f2ca
	v_readlane_b32 s4, v253, 0
	s_add_i32 s6, s4, 0xfffffb00
	s_cmpk_lt_i32 s2, 0x1e0
	v_writelane_b32 v253, s6, 20
	s_cselect_b64 s[8:9], -1, 0
	v_writelane_b32 v253, s8, 21
	s_cmpk_lt_i32 s2, 0x370
	s_movk_i32 s6, 0x6e
	v_writelane_b32 v253, s9, 22
	s_cselect_b64 s[8:9], -1, 0
	v_writelane_b32 v253, s8, 23
	s_cmpk_gt_i32 s2, 0x6f
	v_mov_b64_e32 v[180:181], 0xa0
	v_writelane_b32 v253, s9, 24
	s_cselect_b64 s[8:9], -1, 0
	v_writelane_b32 v253, s8, 25
	s_addk_i32 s4, 0xfc80
	s_cmp_lt_i32 s7, 0
	v_writelane_b32 v253, s9, 26
	v_writelane_b32 v253, s4, 27
	s_cselect_b32 s4, 26, 25
	s_mul_i32 s4, s7, s4
	s_cselect_b32 s8, 31, 30
	s_cselect_b32 s9, 43, 42
	s_cselect_b32 s10, 21, 20
	s_cselect_b32 s11, 61, 60
	s_cselect_b32 s12, 0x6f, s6
	s_add_i32 s4, s4, s5
	s_mul_hi_i32 s6, s4, 0x66666667
	s_lshr_b32 s13, s6, 31
	s_ashr_i32 s6, s6, 4
	s_add_i32 s6, s6, s13
	s_mul_i32 s13, s6, 40
	s_sub_i32 s4, s4, s13
	s_lshl_b32 s14, s6, 3
	s_bfe_i32 s6, s4, 0x80000
	s_bfe_u32 s6, s6, 0x3000c
	s_add_i32 s13, s4, s6
	s_bfe_i32 s6, s13, 0x80000
	s_and_b32 s13, s13, 0xf8
	s_sub_i32 s4, s4, s13
	s_sext_i32_i16 s15, s6
	s_sext_i32_i8 s4, s4
	s_mul_i32 s8, s7, s8
	s_add_i32 s19, s14, s4
	s_ashr_i32 s4, s15, 3
	s_add_i32 s8, s8, s5
	v_writelane_b32 v253, s4, 28
	s_mul_hi_i32 s4, s8, 0x2aaaaaab
	s_lshr_b32 s13, s4, 31
	s_ashr_i32 s4, s4, 3
	s_add_i32 s4, s4, s13
	s_mul_i32 s13, s4, 48
	s_sub_i32 s8, s8, s13
	s_lshl_b32 s14, s4, 3
	s_bfe_i32 s4, s8, 0x80000
	s_bfe_u32 s4, s4, 0x3000c
	s_add_i32 s13, s8, s4
	s_bfe_i32 s4, s13, 0x80000
	s_and_b32 s13, s13, 0xf8
	s_lshr_b32 s6, s15, 3
	s_sext_i32_i16 s15, s4
	s_sub_i32 s8, s8, s13
	s_lshr_b32 s4, s15, 3
	s_sext_i32_i8 s8, s8
	s_add_i32 s8, s14, s8
	s_ashr_i32 s13, s15, 3
	s_bfe_i64 s[14:15], s[4:5], 0x100000
	s_mul_i32 s4, s7, s9
	s_add_i32 s4, s4, s5
	s_ashr_i32 s9, s4, 31
	v_writelane_b32 v253, s13, 29
	s_lshr_b32 s9, s9, 26
	v_writelane_b32 v253, s8, 30
	s_ashr_i32 s8, s8, 31
	s_add_i32 s9, s4, s9
	v_writelane_b32 v253, s8, 31
	s_mul_i32 s8, s7, s10
	s_ashr_i32 s10, s9, 6
	s_andn2_b32 s9, s9, 63
	s_sub_i32 s9, s4, s9
	s_add_i32 s4, s8, s5
	s_mov_b32 s100, s4
	s_mov_b32 s101, 0
	s_ashr_i32 s8, s4, 31
	s_lshl_b32 s13, s10, 3
	s_lshr_b32 s8, s8, 27
	v_writelane_b32 v253, s14, 32
	s_sub_i32 s10, 42, s13
	s_add_i32 s8, s4, s8
	v_writelane_b32 v253, s15, 33
	s_min_u32 s14, s10, 8
	s_ashr_i32 s10, s8, 5
	s_and_b32 s8, s8, 0xffe0
	s_sub_i32 s8, s4, s8
	s_bfe_i32 s4, s8, 0x80000
	s_bfe_u32 s4, s4, 0x3000c
	s_add_i32 s15, s8, s4
	s_bfe_i32 s4, s15, 0x80000
	s_and_b32 s15, s15, 0xf8
	s_sub_i32 s8, s8, s15
	s_lshl_b32 s10, s10, 3
	s_sext_i32_i16 s18, s4
	s_and_b32 s18, s100, 3
	s_lshl_b32 s18, s18, 3
	s_sext_i32_i8 s8, s8
	s_mul_i32 s11, s7, s11
	s_add_i32 s22, s10, s8
	s_lshr_b32 s22, s100, 2
	s_ashr_i32 s8, s18, 3
	s_add_i32 s11, s11, s5
	v_writelane_b32 v253, s8, 34
	s_mul_hi_i32 s8, s11, 0x2aaaaaab
	s_lshr_b32 s10, s8, 31
	s_ashr_i32 s8, s8, 4
	s_add_i32 s8, s8, s10
	s_mul_i32 s10, s8, 0x60
	s_sub_i32 s10, s11, s10
	s_lshl_b32 s15, s8, 3
	s_bfe_i32 s8, s10, 0x80000
	s_bfe_u32 s8, s8, 0x3000c
	s_add_i32 s11, s10, s8
	s_bfe_i32 s8, s11, 0x80000
	s_and_b32 s11, s11, 0xf8
	s_sub_i32 s10, s10, s11
	s_mul_i32 s7, s7, s12
	s_lshr_b32 s4, s18, 3
	s_sext_i32_i16 s18, s8
	s_sext_i32_i8 s10, s10
	s_add_i32 s7, s7, s5
	s_add_i32 s15, s15, s10
	s_ashr_i32 s10, s18, 3
	s_mul_hi_i32 s5, s7, 0x2e8ba2e9
	v_writelane_b32 v253, s10, 35
	s_lshr_b32 s10, s5, 31
	s_ashr_i32 s5, s5, 5
	s_add_i32 s5, s5, s10
	s_lshl_b32 s11, s5, 3
	s_mulk_i32 s5, 0xb0
	s_sub_i32 s5, s7, s5
	s_bfe_u32 s7, s5, 0x3001c
	s_add_i32 s7, s5, s7
	s_sext_i32_i16 s12, s7
	s_and_b32 s7, s7, 0xfff8
	s_sub_i32 s5, s5, s7
	s_sext_i32_i16 s5, s5
	s_ashr_i32 s7, s12, 3
	s_add_i32 s5, s11, s5
	v_writelane_b32 v253, s7, 36
	s_lshr_b32 s10, s12, 3
	v_writelane_b32 v253, s5, 37
	s_ashr_i32 s5, s5, 31
	v_writelane_b32 v253, s5, 38
	s_bfe_i64 s[10:11], s[10:11], 0x100000
	v_writelane_b32 v253, s10, 39
	s_ashr_i32 s5, s19, 31
	s_bfe_i64 s[6:7], s[6:7], 0x100000
	v_writelane_b32 v253, s11, 40
	v_writelane_b32 v253, s19, 41
	v_writelane_b32 v253, s5, 42
	v_writelane_b32 v253, s6, 43
	v_cvt_f32_ubyte0_e32 v1, s14
	s_ashr_i32 s5, s22, 31
	v_writelane_b32 v253, s7, 44
	v_writelane_b32 v253, s22, 45
	s_waitcnt lgkmcnt(0)
	v_cvt_f32_i32_e32 v0, s9
	v_rcp_iflag_f32_e32 v2, v1
	v_writelane_b32 v253, s5, 46
	s_bfe_i64 s[4:5], s[4:5], 0x100000
	v_writelane_b32 v253, s4, 47
	s_lshr_b32 s8, s18, 3
	v_mul_f32_e32 v2, v0, v2
	v_writelane_b32 v253, s5, 48
	v_writelane_b32 v253, s15, 49
	s_ashr_i32 s4, s15, 31
	v_writelane_b32 v253, s4, 50
	s_bfe_i64 s[4:5], s[8:9], 0x100000
	v_trunc_f32_e32 v2, v2
	v_writelane_b32 v253, s4, 51
	v_fma_f32 v0, -v2, v1, v0
	v_cvt_i32_f32_e32 v2, v2
	v_writelane_b32 v253, s5, 52
	s_ashr_i32 s4, s9, 30
	s_or_b32 s6, s4, 1
	v_cmp_ge_f32_e64 s[4:5], |v0|, v1
	s_and_b64 s[4:5], s[4:5], exec
	s_cselect_b32 s4, s6, 0
	v_readfirstlane_b32 s5, v2
	s_add_i32 s4, s5, s4
	s_sext_i32_i8 s5, s4
	s_mul_i32 s4, s4, s14
	s_sub_i32 s4, s9, s4
	s_sext_i32_i8 s4, s4
	v_writelane_b32 v253, s5, 53
	s_add_i32 s4, s13, s4
	v_writelane_b32 v253, s4, 54
	s_lshl_b32 s4, s66, 4
	v_writelane_b32 v253, s4, 6
	s_lshl_b32 s4, s66, 5
	v_writelane_b32 v253, s4, 55
	s_mul_i32 s4, s66, 0xf000
	s_mul_hi_i32 s5, s64, 0x600
	v_writelane_b32 v253, s4, 56
	s_ashr_i32 s65, s64, 31
	s_lshl_b64 s[6:7], s[64:65], 7
	v_writelane_b32 v253, s5, 57
	s_mul_i32 s4, s66, 0x29400
	s_mul_hi_i32 s5, s64, 0x1080
	v_writelane_b32 v253, s4, 58
	s_movk_i32 s19, 0xc00
	s_movk_i32 s18, 0x2000
	v_writelane_b32 v253, s5, 59
	s_add_i32 s4, 0, 0x20020
	v_writelane_b32 v253, s4, 60
	s_add_i32 s4, 0, 0x20024
	v_writelane_b32 v253, s4, 61
	s_mov_b32 s4, 0
	v_writelane_b32 v253, s4, 62
	v_writelane_b32 v253, s6, 63
	s_movk_i32 s5, 0x1f70
	s_mov_b32 s4, s64
	v_writelane_b32 v254, s7, 0
	s_lshl_b64 s[6:7], s[64:65], 2
	v_writelane_b32 v254, s6, 1
	v_writelane_b32 v253, s4, 7
	v_mov_b32_e32 v1, 0
	v_writelane_b32 v254, s7, 2
	s_lshl_b64 s[6:7], s[64:65], 9
	v_writelane_b32 v254, s6, 3
	v_mov_b64_e32 v[182:183], 0x9f
	v_mov_b64_e32 v[184:185], 0x1e0
	v_writelane_b32 v254, s7, 4
	v_writelane_b32 v254, s56, 5
	v_mov_b64_e32 v[186:187], 0x1df
	v_mov_b64_e32 v[188:189], 0x370
	v_writelane_b32 v254, s57, 6
	v_mov_b64_e32 v[190:191], 0x36f
	s_mov_b32 s51, 0xf149f2ca
	s_mov_b32 s46, 0x3e16c740
	s_movk_i32 s96, 0x1f80
	s_movk_i32 s50, 0x1f60
	s_movk_i32 s66, 0x1f50
	s_movk_i32 s33, 0x1600
	s_mov_b32 s47, 0x2c000
	s_mov_b32 s23, 0x3e38aa3b
	s_mov_b32 s59, 0
	v_writelane_b32 v253, s5, 8
	s_mov_b32 s64, 0x16000
	s_mov_b64 s[24:25], 0
	s_mov_b64 s[72:73], 0x80
	v_writelane_b32 v254, s77, 7
	s_barrier
	s_branch .LBB0_265

.LBB0_1297:
	s_nop 0
	v_readlane_b32 s4, v253, 62
	s_cmp_ge_i32 s4, 0x97a0
	s_cselect_b32 s100, 1, 0
	s_cbranch_scc0 .Lko_entry_done
	s_add_i32 s101, s101, 1
	s_lshr_b32 s4, s2, 3
	s_mul_i32 s6, s4, 0xcccd
	s_lshr_b32 s6, s6, 18
	s_mul_i32 s8, s6, 5
	s_sub_i32 s4, s4, s8
	s_and_b32 s8, s2, 7
	s_mul_i32 s8, s8, 5
	s_add_i32 s4, s4, s8
	s_mov_b32 s8, 0
	s_nop 3
	v_writelane_b32 v253, s6, 36
	v_writelane_b32 v253, s4, 37
	v_writelane_b32 v253, s8, 38
	v_writelane_b32 v253, s6, 39
	v_writelane_b32 v253, s8, 40
	s_nop 1
.Lko_entry_done:
	v_readlane_b32 s28, v253, 23
	s_mov_b64 s[26:27], s[0:1]
	s_mov_b64 s[24:25], s[0:1]
	v_readlane_b32 s4, v254, 33
	s_mov_b64 s[8:9], s[0:1]
	s_mov_b64 s[10:11], s[0:1]
	s_mov_b64 s[12:13], s[0:1]
	v_mov_b32_e32 v14, v226
	v_readlane_b32 s29, v253, 24
	s_xor_b64 s[14:15], s[74:75], -1
	s_or_b32 s35, s87, s4
	s_movk_i32 s6, 0x400
	v_readfirstlane_b32 s40, v14
	s_andn2_b64 vcc, exec, s[28:29]
	s_cbranch_vccnz .LBB0_1318
	v_lshlrev_b32_e32 v0, 4, v14
	v_add_u32_e32 v2, 0x2000, v0
	v_ashrrev_i32_e32 v3, 31, v2
	v_lshrrev_b32_e32 v3, 22, v3
	v_add_u32_e32 v3, v2, v3
	v_ashrrev_i32_e32 v3, 10, v3
	v_mul_i32_i24_e32 v4, 0x400, v3
	v_sub_u32_e32 v2, v2, v4
	s_load_dwordx2 s[26:27], s[26:27], 0xe0
	v_lshrrev_b32_e32 v4, 4, v2
	v_bitop3_b32 v2, v4, v2, 32 bitop3:0x6c
	s_load_dwordx2 s[24:25], s[24:25], 0xe0
	v_ashrrev_i32_e32 v4, 31, v2
	v_lshrrev_b32_e32 v4, 26, v4
	v_add_u32_e32 v4, v2, v4
	v_lshlrev_b32_e32 v6, 3, v3
	s_waitcnt lgkmcnt(0)
	s_add_u32 s22, s26, 0xa4ef000
	v_ashrrev_i32_e32 v5, 6, v4
	v_and_b32_e32 v6, -16, v6
	s_addc_u32 s30, s27, 0
	s_mul_i32 s7, s35, 0xb00000
	v_add_u32_e32 v6, v5, v6
	s_add_u32 s7, s24, s7
	v_and_b32_e32 v5, 3, v5
	s_mov_b32 s24, 0x7fffffe0
	v_lshrrev_b32_e32 v7, 2, v6
	v_lshlrev_b32_e32 v8, 1, v6
	v_lshlrev_b32_e32 v3, 5, v3
	v_and_or_b32 v5, v6, s24, v5
	v_and_b32_e32 v7, 4, v7
	v_and_b32_e32 v8, 24, v8
	v_and_b32_e32 v15, 32, v3
	v_and_b32_e32 v3, 0xc0, v4
	v_or3_b32 v5, v5, v7, v8
	v_sub_u32_e32 v2, v2, v3
	v_mov_b32_e32 v8, 1
	v_ashrrev_i16_sdwa v2, v8, sext(v2) dst_sel:DWORD dst_unused:UNUSED_PAD src0_sel:DWORD src1_sel:BYTE_0
	v_bfe_i32 v16, v2, 0, 16
	v_mul_lo_u32 v5, v5, s6
	v_add_u32_e32 v2, v15, v16
	v_mul_lo_u32 v17, v6, s6
	v_add_lshl_u32 v138, v5, v2, 1
	v_add_lshl_u32 v140, v2, v17, 1
	v_bfe_i32 v2, v14, 27, 1
	v_lshrrev_b32_e32 v2, 22, v2
	v_add_u32_e32 v2, v0, v2
	v_and_b32_e32 v2, 0xfffffc00, v2
	v_sub_u32_e32 v0, v0, v2
	v_lshrrev_b32_e32 v2, 4, v0
	v_ashrrev_i32_e32 v4, 31, v14
	v_bitop3_b32 v0, v2, v0, 32 bitop3:0x6c
	v_lshrrev_b32_e32 v4, 26, v4
	v_ashrrev_i32_e32 v2, 31, v0
	v_add_u32_e32 v4, v14, v4
	s_mul_hi_u32 s4, s35, 0xb00000
	v_lshrrev_b32_e32 v2, 26, v2
	v_ashrrev_i32_e32 v4, 6, v4
	s_addc_u32 s4, s25, s4
	v_add_u32_e32 v2, v0, v2
	v_lshlrev_b32_e32 v5, 3, v4
	s_add_u32 s31, s7, 0x16f000
	v_ashrrev_i32_e32 v3, 6, v2
	v_and_b32_e32 v5, -16, v5
	s_addc_u32 s38, s4, 0
	s_ashr_i32 s7, s6, 31
	v_add_u32_e32 v5, v3, v5
	v_and_b32_e32 v3, 3, v3
	s_load_dwordx2 s[26:27], s[8:9], 0xe0
	s_load_dwordx2 s[28:29], s[10:11], 0xe0
	s_nop 0
	s_load_dwordx2 s[8:9], s[12:13], 0xe0
	s_lshl_b64 s[12:13], s[6:7], 9
	v_and_or_b32 v3, v5, s24, v3
	v_readlane_b32 s24, v253, 38
	v_readlane_b32 s41, v253, 37
	s_mul_i32 s24, s12, s24
	s_mul_hi_u32 s25, s12, s41
	s_add_i32 s37, s25, s24
	s_lshr_b64 s[24:25], s[6:7], 23
	v_readlane_b32 s44, v253, 39
	s_mul_i32 s25, s24, s41
	v_readlane_b32 s45, v253, 40
	v_and_b32_e32 v2, 0xc0, v2
	s_add_i32 s37, s37, s25
	s_mul_i32 s25, s12, s45
	s_mul_hi_u32 s42, s12, s44
	s_ashr_i32 s4, s40, 6
	v_lshrrev_b32_e32 v6, 2, v5
	v_lshlrev_b32_e32 v7, 1, v5
	v_sub_u32_e32 v0, v0, v2
	s_add_i32 s25, s42, s25
	s_mul_i32 s24, s24, s44
	s_ashr_i32 s36, s40, 8
	s_lshl_b64 s[10:11], s[6:7], 8
	s_lshl_b32 s39, s4, 10
	v_and_b32_e32 v6, 4, v6
	v_and_b32_e32 v7, 24, v7
	v_lshlrev_b32_e32 v4, 5, v4
	v_ashrrev_i16_sdwa v0, v8, sext(v0) dst_sel:DWORD dst_unused:UNUSED_PAD src0_sel:DWORD src1_sel:BYTE_0
	s_add_i32 s25, s25, s24
	s_mul_i32 s24, s12, s44
	v_or3_b32 v3, v3, v6, v7
	v_and_b32_e32 v18, 32, v4
	v_bfe_i32 v19, v0, 0, 16
	s_add_u32 s48, s31, s24
	v_mul_lo_u32 v3, v3, s6
	v_add_u32_e32 v2, v18, v19
	s_addc_u32 s49, s38, s25
	s_add_i32 s47, s39, 0
	v_add_lshl_u32 v0, v3, v2, 1
	s_add_i32 m0, s47, 0x10000
	s_mul_i32 s41, s12, s41
	global_load_lds_dwordx4 v0, s[48:49]
	s_add_i32 m0, s47, 0x12000
	s_add_u32 s24, s48, s10
	global_load_lds_dwordx4 v138, s[48:49]
	s_addc_u32 s25, s49, s11
	s_add_i32 m0, s47, 0x14000
	v_mul_lo_u32 v20, v5, s6
	global_load_lds_dwordx4 v0, s[24:25]
	s_add_i32 m0, s47, 0x16000
	s_add_u32 s44, s22, s41
	v_mov_b32_e32 v139, v1
	s_addc_u32 s45, s30, s37
	s_add_i32 s52, s47, 0x2000
	v_add_lshl_u32 v142, v2, v20, 1
	v_lshl_add_u64 v[6:7], s[24:25], 0, v[0:1]
	v_lshl_add_u64 v[8:9], s[24:25], 0, v[138:139]
	global_load_lds_dwordx4 v138, s[24:25]
	s_mov_b32 m0, s47
	s_add_u32 s24, s44, s10
	global_load_lds_dwordx4 v142, s[44:45]
	s_mov_b32 m0, s52
	s_addc_u32 s25, s45, s11
	s_add_i32 s53, s47, 0x4000
	global_load_lds_dwordx4 v140, s[44:45]
	s_mov_b32 m0, s53
	s_add_i32 s54, s47, 0x6000
	global_load_lds_dwordx4 v142, s[24:25]
	s_mov_b32 m0, s54
	v_mov_b32_e32 v143, v1
	global_load_lds_dwordx4 v140, s[24:25]
	v_mov_b32_e32 v141, v1
	s_cmp_eq_u32 s36, 1
	v_mov_b32_e32 v252, 1
	v_lshl_add_u64 v[2:3], s[48:49], 0, v[0:1]
	v_lshl_add_u64 v[4:5], s[48:49], 0, v[138:139]
	v_lshl_add_u64 v[10:11], s[44:45], 0, v[142:143]
	v_lshl_add_u64 v[12:13], s[44:45], 0, v[140:141]
	s_cselect_b64 s[24:25], -1, 0
	s_cmp_lg_u32 s36, 1
	s_cbranch_scc1 .LBB0_1300
	s_barrier

.LBB0_1303:
	s_add_i32 s62, s62, 1
	s_cmp_eq_u32 s100, 0
	s_cbranch_scc1 .Lko_orig
	s_cmp_lt_u32 s62, 3
	s_cbranch_scc0 .Lko_late
	s_lshl_b32 s4, s62, 5
	s_lshr_b32 s6, s2, 3
	s_add_i32 s4, s4, s6
	s_and_b32 s7, s2, 7
	s_cmp_eq_u32 s4, 0x5f
	s_cbranch_scc1 .Lko_95
	s_mul_i32 s6, s4, 0xcccd
	s_lshr_b32 s64, s6, 18
	s_mul_i32 s6, s64, 5
	s_sub_i32 s4, s4, s6
	s_mul_i32 s7, s7, 5
	s_add_i32 s65, s7, s4
	s_branch .Lko_has
.Lko_95:
	s_mov_b32 s64, 19
	s_mov_b32 s65, s7
	s_branch .Lko_has
.Lko_late:
	s_cmp_lt_u32 s2, 0xa0
	s_cbranch_scc1 .Lko_none
	s_sub_i32 s4, s2, 0xa0
	s_cmp_eq_u32 s62, 3
	s_cbranch_scc1 .Lko_d
	s_cmp_eq_u32 s62, 4
	s_cbranch_scc0 .Lko_none
	s_addk_i32 s4, 0x60
	s_cmp_lt_u32 s4, 0x70
	s_cbranch_scc0 .Lko_none
.Lko_d:
	s_cmp_lt_u32 s4, 32
	s_cbranch_scc0 .Lko_d2
	s_add_i32 s65, s4, 8
	s_mov_b32 s64, 19
	s_branch .Lko_has
.Lko_d2:
	s_cmp_lt_u32 s4, 0x48
	s_cbranch_scc0 .Lko_d3
	s_sub_i32 s65, s4, 32
	s_mov_b32 s64, 20
	s_branch .Lko_has
.Lko_d3:
	s_sub_i32 s65, s4, 0x48
	s_mov_b32 s64, 21
.Lko_has:
	s_mov_b64 s[8:9], exec
	s_branch .LBB0_1305
.Lko_none:
	s_mov_b64 s[8:9], 0
	s_branch .LBB0_1305
.Lko_orig:
	s_mul_i32 s4, s62, s17
	s_mul_hi_u32 s6, s62, s16
	s_add_i32 s4, s6, s4
	s_mul_i32 s6, s62, s16
	s_add_u32 s6, s6, s2
	s_addc_u32 s7, s4, s3
	v_cmp_gt_i64_e32 vcc, s[6:7], v[190:191]
	v_cmp_lt_i64_e64 s[8:9], s[6:7], v[188:189]
	s_cbranch_vccnz .LBB0_1305
	s_ashr_i32 s4, s6, 31
	s_lshr_b32 s4, s4, 29
	s_add_i32 s4, s6, s4
	s_ashr_i32 s7, s4, 3
	s_and_b32 s4, s4, -8
	s_sub_i32 s4, s6, s4
	s_cmp_lt_i32 s4, 0
	s_movk_i32 s6, 0x6e
	s_cselect_b32 s6, 0x6f, s6
	s_mul_i32 s4, s4, s6
	s_add_i32 s4, s4, s7
	s_mul_hi_i32 s6, s4, 0x2e8ba2e9
	s_lshr_b32 s7, s6, 31
	s_ashr_i32 s6, s6, 5
	s_add_i32 s6, s6, s7
	s_lshl_b32 s7, s6, 3
	s_sub_i32 s42, 40, s7
	s_min_i32 s42, s42, 8
	s_abs_i32 s43, s42
	v_cvt_f32_u32_e32 v2, s43
	s_sub_i32 s65, 0, s43
	s_mulk_i32 s6, 0xb0
	s_sub_i32 s4, s4, s6
	v_rcp_iflag_f32_e32 v2, v2
	s_abs_i32 s6, s4
	s_xor_b32 s64, s4, s42
	s_ashr_i32 s64, s64, 31
	v_mul_f32_e32 v2, 0x4f7ffffe, v2
	v_cvt_u32_f32_e32 v2, v2
	s_nop 0
	v_readfirstlane_b32 s69, v2
	s_mul_i32 s65, s65, s69
	s_mul_hi_u32 s65, s69, s65
	s_add_i32 s69, s69, s65
	s_mul_hi_u32 s65, s6, s69
	s_mul_i32 s69, s65, s43
	s_sub_i32 s6, s6, s69
	s_add_i32 s70, s65, 1
	s_sub_i32 s69, s6, s43
	s_cmp_ge_u32 s6, s43
	s_cselect_b32 s65, s70, s65
	s_cselect_b32 s6, s69, s6
	s_add_i32 s69, s65, 1
	s_cmp_ge_u32 s6, s43
	s_cselect_b32 s6, s69, s65
	s_xor_b32 s6, s6, s64
	s_sub_i32 s64, s6, s64
	s_mul_i32 s6, s64, s42
	s_sub_i32 s4, s4, s6
	s_add_i32 s65, s7, s4

.LBB0_1314:
	s_lshl_b32 s4, s68, 8
	v_add_u32_e32 v172, s4, v151
	s_addk_i32 s4, 0xe000
	s_lshr_b32 s4, s4, 10
	s_add_i32 s4, s4, 1
	s_cmp_gt_i32 s68, 31
	s_cselect_b32 s4, s4, 0
	s_mul_hi_u32 s44, s4, 0x5800
	s_mulk_i32 s4, 0x5800
	s_add_u32 s4, s55, s4
	s_addc_u32 s48, s56, s44
	s_lshl_b32 s44, s67, 8
	s_ashr_i32 s45, s44, 31
	s_lshl_b64 s[44:45], s[44:45], 2
	v_ashrrev_i32_e32 v173, 31, v172
	s_add_u32 s4, s4, s44
	v_lshl_add_u64 v[130:131], v[172:173], 2, s[28:29]
	s_addc_u32 s45, s48, s45
	global_load_dword v148, v[130:131], off
	global_load_dword v149, v[130:131], off offset:64
	global_load_dword v150, v[130:131], off offset:128
	global_load_dword v152, v[130:131], off offset:192
	global_load_dword v154, v[130:131], off offset:512
	global_load_dword v156, v[130:131], off offset:576
	global_load_dword v158, v[130:131], off offset:640
	global_load_dword v163, v[130:131], off offset:704
	s_add_u32 s44, s4, s63
	s_addc_u32 s45, s45, 0
	global_load_dwordx4 v[164:167], v159, s[44:45] offset:512
	global_load_dwordx4 v[134:137], v159, s[44:45]
	global_load_dwordx4 v[168:171], v159, s[44:45] offset:528
	global_load_dwordx4 v[130:133], v159, s[44:45] offset:16
	v_mov_b32_e32 v194, v122
	v_mov_b32_e32 v177, v118
	v_mov_b32_e32 v118, v127
	v_mov_b32_e32 v196, v124
	v_or_b32_e32 v199, 48, v172
	v_mov_b32_e32 v176, v126
	v_mov_b32_e32 v193, v120
	v_mov_b32_e32 v120, v129
	v_mov_b32_e32 v192, v128
	v_mov_b32_e32 v195, v114
	v_mov_b32_e32 v197, v116
	v_mov_b32_e32 v116, v125
	v_mov_b32_e32 v114, v123
	v_lshl_or_b32 v174, s67, 7, v155
	v_ashrrev_i32_e32 v175, 31, v174
	v_or_b32_e32 v173, 16, v172
	v_or_b32_e32 v179, 32, v172
	v_add_u32_e32 v162, 0x80, v172
	v_add_u32_e32 v161, 0x90, v172
	v_add_u32_e32 v160, 0xa0, v172
	v_add_u32_e32 v123, 0xb0, v172
	s_and_b64 vcc, exec, s[6:7]
	s_mov_b64 s[6:7], -1
	s_waitcnt vmcnt(0)
	v_fmamk_f32 v122, v148, 0x3a800000, v227
	v_rsq_f32_e32 v198, v122
	v_fmamk_f32 v124, v149, 0x3a800000, v227
	v_fmamk_f32 v126, v152, 0x3a800000, v227
	v_fmamk_f32 v127, v154, 0x3a800000, v227
	v_fmamk_f32 v125, v150, 0x3a800000, v227
	v_fmamk_f32 v129, v158, 0x3a800000, v227
	v_fmamk_f32 v148, v163, 0x3a800000, v227
	v_mov_b32_e32 v149, v134
	v_mov_b32_e32 v134, v165
	v_rsq_f32_e32 v122, v148
	v_mov_b32_e32 v148, v164
	v_pk_fma_f32 v[118:119], v[118:119], v[198:199], v[134:135] op_sel_hi:[1,0,1]
	v_pk_fma_f32 v[164:165], v[176:177], v[198:199], v[148:149] op_sel_hi:[1,0,1]
	v_mul_f32_e32 v176, 0xbfb8aa3b, v119
	v_exp_f32_e32 v176, v176
	v_mul_f32_e32 v163, 0xbfb8aa3b, v165
	v_exp_f32_e32 v163, v163
	v_fmamk_f32 v128, v156, 0x3a800000, v227
	v_add_f32_e32 v176, 1.0, v176
	v_rcp_f32_e32 v176, v176
	v_rsq_f32_e32 v156, v126
	v_rsq_f32_e32 v154, v127
	v_rsq_f32_e32 v150, v129
	v_mov_b32_e32 v129, v136
	v_mov_b32_e32 v136, v167
	v_mov_b32_e32 v126, v168
	v_mov_b32_e32 v127, v130
	v_rsq_f32_e32 v152, v128
	v_mov_b32_e32 v128, v166
	v_mov_b32_e32 v130, v169
	v_pk_fma_f32 v[120:121], v[120:121], v[198:199], v[136:137] op_sel_hi:[1,0,1]
	v_pk_fma_f32 v[168:169], v[194:195], v[198:199], v[126:127] op_sel_hi:[1,0,1]
	v_mul_f32_e32 v119, v119, v176
	v_pk_fma_f32 v[166:167], v[192:193], v[198:199], v[128:129] op_sel_hi:[1,0,1]
	v_mul_f32_e32 v192, 0xbfb8aa3b, v121
	v_mul_f32_e32 v118, v118, v119
	v_mul_f32_e32 v119, 0xbfb8aa3b, v169
	v_mul_f32_e32 v177, 0xbfb8aa3b, v167
	v_exp_f32_e32 v192, v192
	v_add_f32_e32 v163, 1.0, v163
	v_exp_f32_e32 v119, v119
	v_exp_f32_e32 v177, v177
	v_rcp_f32_e32 v163, v163
	v_pk_fma_f32 v[114:115], v[114:115], v[198:199], v[130:131] op_sel_hi:[1,0,1]
	v_add_f32_e32 v192, 1.0, v192
	v_add_f32_e32 v119, 1.0, v119
	v_add_f32_e32 v177, 1.0, v177
	v_rcp_f32_e32 v192, v192
	v_mul_f32_e32 v163, v165, v163
	v_rcp_f32_e32 v119, v119
	v_mul_f32_e32 v165, 0xbfb8aa3b, v115
	v_rcp_f32_e32 v177, v177
	v_exp_f32_e32 v165, v165
	v_rsq_f32_e32 v200, v124
	v_rsq_f32_e32 v158, v125
	v_mov_b32_e32 v124, v170
	v_mov_b32_e32 v125, v132
	v_mov_b32_e32 v132, v171
	v_pk_fma_f32 v[170:171], v[196:197], v[198:199], v[124:125] op_sel_hi:[1,0,1]
	v_mul_f32_e32 v121, v121, v192
	v_mul_f32_e32 v119, v169, v119
	v_pk_fma_f32 v[116:117], v[116:117], v[198:199], v[132:133] op_sel_hi:[1,0,1]
	v_mul_f32_e32 v163, v164, v163
	v_mul_f32_e32 v164, v167, v177
	v_mul_f32_e32 v120, v120, v121
	v_mul_f32_e32 v121, v168, v119
	v_add_f32_e32 v119, 1.0, v165
	v_mul_f32_e32 v165, 0xbfb8aa3b, v171
	v_mul_f32_e32 v164, v166, v164
	v_rcp_f32_e32 v119, v119
	v_exp_f32_e32 v165, v165
	v_mul_f32_e32 v166, 0xbfb8aa3b, v117
	v_exp_f32_e32 v166, v166
	v_mul_f32_e32 v115, v115, v119
	v_add_f32_e32 v119, 1.0, v165
	v_rcp_f32_e32 v119, v119
	v_add_f32_e32 v165, 1.0, v166
	v_rcp_f32_e32 v165, v165
	v_mul_f32_e32 v114, v114, v115
	v_mul_f32_e32 v115, v171, v119
	v_mul_f32_e32 v115, v170, v115
	v_mul_f32_e32 v117, v117, v165
	v_mul_f32_e32 v116, v116, v117
	v_cvt_pk_bf16_f32 v118, v163, v118
	v_cvt_pk_bf16_f32 v119, v164, v120
	v_cvt_pk_bf16_f32 v120, v121, v114
	v_cvt_pk_bf16_f32 v121, v115, v116
	v_mov_b64_e32 v[114:115], s[26:27]
	v_mad_i64_i32 v[164:165], s[44:45], v172, s33, v[114:115]
	v_lshlrev_b64 v[116:117], 1, v[174:175]
	v_lshl_add_u64 v[164:165], v[164:165], 0, v[116:117]
	global_store_dwordx4 v[164:165], v[118:121], off
	s_nop 1
	v_mov_b32_e32 v118, v110
	v_mov_b32_e32 v119, v106
	v_pk_fma_f32 v[118:119], v[118:119], v[200:201], v[148:149] op_sel_hi:[1,0,1]
	v_mov_b32_e32 v106, v111
	v_pk_fma_f32 v[106:107], v[106:107], v[200:201], v[134:135] op_sel_hi:[1,0,1]
	v_mov_b32_e32 v111, v108
	v_mov_b32_e32 v108, v113
	v_mov_b32_e32 v113, v98
	v_mov_b32_e32 v98, v103
	v_mov_b32_e32 v103, v100
	v_mul_f32_e32 v100, 0xbfb8aa3b, v119
	v_mov_b32_e32 v110, v112
	v_mov_b32_e32 v112, v102
	v_mov_b32_e32 v102, v104
	v_exp_f32_e32 v104, v100
	v_mul_f32_e32 v100, 0xbfb8aa3b, v107
	v_exp_f32_e32 v120, v100
	v_mov_b32_e32 v100, v105
	v_add_f32_e32 v104, 1.0, v104
	v_rcp_f32_e32 v104, v104
	v_add_f32_e32 v105, 1.0, v120
	v_rcp_f32_e32 v105, v105
	v_pk_fma_f32 v[110:111], v[110:111], v[200:201], v[128:129] op_sel_hi:[1,0,1]
	v_pk_fma_f32 v[108:109], v[108:109], v[200:201], v[136:137] op_sel_hi:[1,0,1]
	v_mul_f32_e32 v104, v119, v104
	v_mul_f32_e32 v105, v107, v105
	v_mul_f32_e32 v107, 0xbfb8aa3b, v111
	v_mul_f32_e32 v104, v118, v104
	v_exp_f32_e32 v107, v107
	v_mul_f32_e32 v118, 0xbfb8aa3b, v109
	v_exp_f32_e32 v118, v118
	v_pk_fma_f32 v[112:113], v[112:113], v[200:201], v[126:127] op_sel_hi:[1,0,1]
	v_mul_f32_e32 v105, v106, v105
	v_add_f32_e32 v106, 1.0, v107
	v_rcp_f32_e32 v106, v106
	v_add_f32_e32 v107, 1.0, v118
	v_mul_f32_e32 v118, 0xbfb8aa3b, v113
	v_rcp_f32_e32 v107, v107
	v_exp_f32_e32 v118, v118
	v_pk_fma_f32 v[98:99], v[98:99], v[200:201], v[130:131] op_sel_hi:[1,0,1]
	v_mul_f32_e32 v106, v111, v106
	v_mul_f32_e32 v106, v110, v106
	v_mul_f32_e32 v107, v109, v107
	v_add_f32_e32 v109, 1.0, v118
	v_mul_f32_e32 v110, 0xbfb8aa3b, v99
	v_rcp_f32_e32 v109, v109
	v_exp_f32_e32 v110, v110
	v_pk_fma_f32 v[102:103], v[102:103], v[200:201], v[124:125] op_sel_hi:[1,0,1]
	v_pk_fma_f32 v[100:101], v[100:101], v[200:201], v[132:133] op_sel_hi:[1,0,1]
	v_mul_f32_e32 v107, v108, v107
	v_mul_f32_e32 v108, v113, v109
	v_add_f32_e32 v109, 1.0, v110
	v_mul_f32_e32 v110, 0xbfb8aa3b, v103
	v_rcp_f32_e32 v109, v109
	v_exp_f32_e32 v110, v110
	v_mul_f32_e32 v111, 0xbfb8aa3b, v101
	v_exp_f32_e32 v111, v111
	v_mul_f32_e32 v99, v99, v109
	v_add_f32_e32 v109, 1.0, v110
	v_rcp_f32_e32 v109, v109
	v_add_f32_e32 v110, 1.0, v111
	v_rcp_f32_e32 v110, v110
	v_mul_f32_e32 v111, v98, v99
	v_mul_f32_e32 v98, v103, v109
	v_mul_f32_e32 v102, v102, v98
	v_mul_f32_e32 v98, v101, v110
	v_mul_f32_e32 v101, v100, v98
	v_mul_f32_e32 v108, v112, v108
	v_cvt_pk_bf16_f32 v98, v104, v105
	v_cvt_pk_bf16_f32 v99, v106, v107
	v_cvt_pk_bf16_f32 v100, v108, v111
	v_cvt_pk_bf16_f32 v101, v102, v101
	v_mad_i64_i32 v[102:103], s[44:45], v173, s33, v[114:115]
	v_lshl_add_u64 v[102:103], v[102:103], 0, v[116:117]
	global_store_dwordx4 v[102:103], v[98:101], off
	s_nop 1
	v_mov_b32_e32 v98, v94
	v_mov_b32_e32 v99, v90
	v_pk_fma_f32 v[98:99], v[98:99], v[158:159], v[148:149] op_sel_hi:[1,0,1]
	v_mov_b32_e32 v90, v95
	v_pk_fma_f32 v[90:91], v[90:91], v[158:159], v[134:135] op_sel_hi:[1,0,1]
	v_mov_b32_e32 v95, v92
	v_mov_b32_e32 v92, v97
	v_mov_b32_e32 v97, v82
	v_mov_b32_e32 v82, v87
	v_mov_b32_e32 v87, v84
	v_mul_f32_e32 v84, 0xbfb8aa3b, v99
	v_mov_b32_e32 v94, v96
	v_mov_b32_e32 v96, v86
	v_mov_b32_e32 v86, v88
	v_exp_f32_e32 v88, v84
	v_mul_f32_e32 v84, 0xbfb8aa3b, v91
	v_exp_f32_e32 v100, v84
	v_mov_b32_e32 v84, v89
	v_add_f32_e32 v88, 1.0, v88
	v_rcp_f32_e32 v88, v88
	v_add_f32_e32 v89, 1.0, v100
	v_rcp_f32_e32 v89, v89
	v_pk_fma_f32 v[94:95], v[94:95], v[158:159], v[128:129] op_sel_hi:[1,0,1]
	v_pk_fma_f32 v[92:93], v[92:93], v[158:159], v[136:137] op_sel_hi:[1,0,1]
	v_mul_f32_e32 v88, v99, v88
	v_mul_f32_e32 v89, v91, v89
	v_mul_f32_e32 v91, 0xbfb8aa3b, v95
	v_mul_f32_e32 v88, v98, v88
	v_exp_f32_e32 v91, v91
	v_mul_f32_e32 v98, 0xbfb8aa3b, v93
	v_exp_f32_e32 v98, v98
	v_pk_fma_f32 v[96:97], v[96:97], v[158:159], v[126:127] op_sel_hi:[1,0,1]
	v_mul_f32_e32 v89, v90, v89
	v_add_f32_e32 v90, 1.0, v91
	v_rcp_f32_e32 v90, v90
	v_add_f32_e32 v91, 1.0, v98
	v_mul_f32_e32 v98, 0xbfb8aa3b, v97
	v_rcp_f32_e32 v91, v91
	v_exp_f32_e32 v98, v98
	v_pk_fma_f32 v[82:83], v[82:83], v[158:159], v[130:131] op_sel_hi:[1,0,1]
	v_mul_f32_e32 v90, v95, v90
	v_mul_f32_e32 v90, v94, v90
	v_mul_f32_e32 v91, v93, v91
	v_add_f32_e32 v93, 1.0, v98
	v_mul_f32_e32 v94, 0xbfb8aa3b, v83
	v_rcp_f32_e32 v93, v93
	v_exp_f32_e32 v94, v94
	v_pk_fma_f32 v[86:87], v[86:87], v[158:159], v[124:125] op_sel_hi:[1,0,1]
	v_pk_fma_f32 v[84:85], v[84:85], v[158:159], v[132:133] op_sel_hi:[1,0,1]
	v_mul_f32_e32 v91, v92, v91
	v_mul_f32_e32 v92, v97, v93
	v_add_f32_e32 v93, 1.0, v94
	v_mul_f32_e32 v94, 0xbfb8aa3b, v87
	v_rcp_f32_e32 v93, v93
	v_exp_f32_e32 v94, v94
	v_mul_f32_e32 v95, 0xbfb8aa3b, v85
	v_exp_f32_e32 v95, v95
	v_mul_f32_e32 v83, v83, v93
	v_add_f32_e32 v93, 1.0, v94
	v_rcp_f32_e32 v93, v93
	v_add_f32_e32 v94, 1.0, v95
	v_rcp_f32_e32 v94, v94
	v_mul_f32_e32 v95, v82, v83
	v_mul_f32_e32 v82, v87, v93
	v_mul_f32_e32 v86, v86, v82
	v_mul_f32_e32 v82, v85, v94
	v_mul_f32_e32 v85, v84, v82
	v_mul_f32_e32 v92, v96, v92
	v_cvt_pk_bf16_f32 v82, v88, v89
	v_cvt_pk_bf16_f32 v83, v90, v91
	v_cvt_pk_bf16_f32 v84, v92, v95
	v_cvt_pk_bf16_f32 v85, v86, v85
	v_mad_i64_i32 v[86:87], s[44:45], v179, s33, v[114:115]
	v_lshl_add_u64 v[86:87], v[86:87], 0, v[116:117]
	global_store_dwordx4 v[86:87], v[82:85], off
	s_nop 1
	v_mov_b32_e32 v82, v78
	v_mov_b32_e32 v83, v74
	v_pk_fma_f32 v[82:83], v[82:83], v[156:157], v[148:149] op_sel_hi:[1,0,1]
	v_mov_b32_e32 v74, v79
	v_pk_fma_f32 v[74:75], v[74:75], v[156:157], v[134:135] op_sel_hi:[1,0,1]
	v_mov_b32_e32 v79, v76
	v_mov_b32_e32 v76, v81
	v_mov_b32_e32 v81, v66
	v_mov_b32_e32 v66, v71
	v_mov_b32_e32 v71, v68
	v_mul_f32_e32 v68, 0xbfb8aa3b, v83
	v_mov_b32_e32 v78, v80
	v_mov_b32_e32 v80, v70
	v_mov_b32_e32 v70, v72
	v_exp_f32_e32 v72, v68
	v_mul_f32_e32 v68, 0xbfb8aa3b, v75
	v_exp_f32_e32 v84, v68
	v_mov_b32_e32 v68, v73
	v_add_f32_e32 v72, 1.0, v72
	v_rcp_f32_e32 v72, v72
	v_add_f32_e32 v73, 1.0, v84
	v_rcp_f32_e32 v73, v73
	v_pk_fma_f32 v[78:79], v[78:79], v[156:157], v[128:129] op_sel_hi:[1,0,1]
	v_pk_fma_f32 v[76:77], v[76:77], v[156:157], v[136:137] op_sel_hi:[1,0,1]
	v_mul_f32_e32 v72, v83, v72
	v_mul_f32_e32 v73, v75, v73
	v_mul_f32_e32 v75, 0xbfb8aa3b, v79
	v_mul_f32_e32 v72, v82, v72
	v_exp_f32_e32 v75, v75
	v_mul_f32_e32 v82, 0xbfb8aa3b, v77
	v_exp_f32_e32 v82, v82
	v_pk_fma_f32 v[80:81], v[80:81], v[156:157], v[126:127] op_sel_hi:[1,0,1]
	v_mul_f32_e32 v73, v74, v73
	v_add_f32_e32 v74, 1.0, v75
	v_rcp_f32_e32 v74, v74
	v_add_f32_e32 v75, 1.0, v82
	v_mul_f32_e32 v82, 0xbfb8aa3b, v81
	v_rcp_f32_e32 v75, v75
	v_exp_f32_e32 v82, v82
	v_pk_fma_f32 v[66:67], v[66:67], v[156:157], v[130:131] op_sel_hi:[1,0,1]
	v_mul_f32_e32 v74, v79, v74
	v_mul_f32_e32 v74, v78, v74
	v_mul_f32_e32 v75, v77, v75
	v_add_f32_e32 v77, 1.0, v82
	v_mul_f32_e32 v78, 0xbfb8aa3b, v67
	v_rcp_f32_e32 v77, v77
	v_exp_f32_e32 v78, v78
	v_pk_fma_f32 v[70:71], v[70:71], v[156:157], v[124:125] op_sel_hi:[1,0,1]
	v_pk_fma_f32 v[68:69], v[68:69], v[156:157], v[132:133] op_sel_hi:[1,0,1]
	v_mul_f32_e32 v75, v76, v75
	v_mul_f32_e32 v76, v81, v77
	v_add_f32_e32 v77, 1.0, v78
	v_mul_f32_e32 v78, 0xbfb8aa3b, v71
	v_rcp_f32_e32 v77, v77
	v_exp_f32_e32 v78, v78
	v_mul_f32_e32 v79, 0xbfb8aa3b, v69
	v_exp_f32_e32 v79, v79
	v_mul_f32_e32 v67, v67, v77
	v_add_f32_e32 v77, 1.0, v78
	v_rcp_f32_e32 v77, v77
	v_add_f32_e32 v78, 1.0, v79
	v_rcp_f32_e32 v78, v78
	v_mul_f32_e32 v79, v66, v67
	v_mul_f32_e32 v66, v71, v77
	v_mul_f32_e32 v70, v70, v66
	v_mul_f32_e32 v66, v69, v78
	v_mul_f32_e32 v69, v68, v66
	v_mul_f32_e32 v76, v80, v76
	v_cvt_pk_bf16_f32 v66, v72, v73
	v_cvt_pk_bf16_f32 v67, v74, v75
	v_cvt_pk_bf16_f32 v68, v76, v79
	v_cvt_pk_bf16_f32 v69, v70, v69
	v_mad_i64_i32 v[70:71], s[44:45], v199, s33, v[114:115]
	v_lshl_add_u64 v[70:71], v[70:71], 0, v[116:117]
	global_store_dwordx4 v[70:71], v[66:69], off
	s_nop 1
	v_mov_b32_e32 v66, v62
	v_mov_b32_e32 v67, v58
	v_pk_fma_f32 v[66:67], v[66:67], v[154:155], v[148:149] op_sel_hi:[1,0,1]
	v_mov_b32_e32 v58, v63
	v_pk_fma_f32 v[58:59], v[58:59], v[154:155], v[134:135] op_sel_hi:[1,0,1]
	v_mov_b32_e32 v63, v60
	v_mov_b32_e32 v60, v65
	v_mov_b32_e32 v65, v50
	v_mov_b32_e32 v50, v55
	v_mov_b32_e32 v55, v52
	v_mul_f32_e32 v52, 0xbfb8aa3b, v67
	v_mov_b32_e32 v62, v64
	v_mov_b32_e32 v64, v54
	v_mov_b32_e32 v54, v56
	v_exp_f32_e32 v56, v52
	v_mul_f32_e32 v52, 0xbfb8aa3b, v59
	v_exp_f32_e32 v68, v52
	v_mov_b32_e32 v52, v57
	v_add_f32_e32 v56, 1.0, v56
	v_rcp_f32_e32 v56, v56
	v_add_f32_e32 v57, 1.0, v68
	v_rcp_f32_e32 v57, v57
	v_pk_fma_f32 v[62:63], v[62:63], v[154:155], v[128:129] op_sel_hi:[1,0,1]
	v_pk_fma_f32 v[60:61], v[60:61], v[154:155], v[136:137] op_sel_hi:[1,0,1]
	v_mul_f32_e32 v56, v67, v56
	v_mul_f32_e32 v57, v59, v57
	v_mul_f32_e32 v59, 0xbfb8aa3b, v63
	v_mul_f32_e32 v56, v66, v56
	v_exp_f32_e32 v59, v59
	v_mul_f32_e32 v66, 0xbfb8aa3b, v61
	v_exp_f32_e32 v66, v66
	v_pk_fma_f32 v[64:65], v[64:65], v[154:155], v[126:127] op_sel_hi:[1,0,1]
	v_mul_f32_e32 v57, v58, v57
	v_add_f32_e32 v58, 1.0, v59
	v_rcp_f32_e32 v58, v58
	v_add_f32_e32 v59, 1.0, v66
	v_mul_f32_e32 v66, 0xbfb8aa3b, v65
	v_rcp_f32_e32 v59, v59
	v_exp_f32_e32 v66, v66
	v_pk_fma_f32 v[50:51], v[50:51], v[154:155], v[130:131] op_sel_hi:[1,0,1]
	v_mul_f32_e32 v58, v63, v58
	v_mul_f32_e32 v58, v62, v58
	v_mul_f32_e32 v59, v61, v59
	v_add_f32_e32 v61, 1.0, v66
	v_mul_f32_e32 v62, 0xbfb8aa3b, v51
	v_rcp_f32_e32 v61, v61
	v_exp_f32_e32 v62, v62
	v_pk_fma_f32 v[54:55], v[54:55], v[154:155], v[124:125] op_sel_hi:[1,0,1]
	v_pk_fma_f32 v[52:53], v[52:53], v[154:155], v[132:133] op_sel_hi:[1,0,1]
	v_mul_f32_e32 v59, v60, v59
	v_mul_f32_e32 v60, v65, v61
	v_add_f32_e32 v61, 1.0, v62
	v_mul_f32_e32 v62, 0xbfb8aa3b, v55
	v_rcp_f32_e32 v61, v61
	v_exp_f32_e32 v62, v62
	v_mul_f32_e32 v63, 0xbfb8aa3b, v53
	v_exp_f32_e32 v63, v63
	v_mul_f32_e32 v51, v51, v61
	v_add_f32_e32 v61, 1.0, v62
	v_rcp_f32_e32 v61, v61
	v_add_f32_e32 v62, 1.0, v63
	v_rcp_f32_e32 v62, v62
	v_mul_f32_e32 v63, v50, v51
	v_mul_f32_e32 v50, v55, v61
	v_mul_f32_e32 v54, v54, v50
	v_mul_f32_e32 v50, v53, v62
	v_mul_f32_e32 v53, v52, v50
	v_mul_f32_e32 v60, v64, v60
	v_cvt_pk_bf16_f32 v50, v56, v57
	v_cvt_pk_bf16_f32 v51, v58, v59
	v_cvt_pk_bf16_f32 v52, v60, v63
	v_cvt_pk_bf16_f32 v53, v54, v53
	v_mad_i64_i32 v[54:55], s[44:45], v162, s33, v[114:115]
	v_lshl_add_u64 v[54:55], v[54:55], 0, v[116:117]
	global_store_dwordx4 v[54:55], v[50:53], off
	s_nop 1
	v_mov_b32_e32 v50, v46
	v_mov_b32_e32 v51, v42
	v_pk_fma_f32 v[50:51], v[50:51], v[152:153], v[148:149] op_sel_hi:[1,0,1]
	v_mov_b32_e32 v42, v47
	v_pk_fma_f32 v[42:43], v[42:43], v[152:153], v[134:135] op_sel_hi:[1,0,1]
	v_mov_b32_e32 v47, v44
	v_mov_b32_e32 v44, v49
	v_mov_b32_e32 v49, v34
	v_mov_b32_e32 v34, v39
	v_mov_b32_e32 v39, v36
	v_mul_f32_e32 v36, 0xbfb8aa3b, v51
	v_mov_b32_e32 v46, v48
	v_mov_b32_e32 v48, v38
	v_mov_b32_e32 v38, v40
	v_exp_f32_e32 v40, v36
	v_mul_f32_e32 v36, 0xbfb8aa3b, v43
	v_exp_f32_e32 v52, v36
	v_mov_b32_e32 v36, v41
	v_add_f32_e32 v40, 1.0, v40
	v_rcp_f32_e32 v40, v40
	v_add_f32_e32 v41, 1.0, v52
	v_rcp_f32_e32 v41, v41
	v_pk_fma_f32 v[46:47], v[46:47], v[152:153], v[128:129] op_sel_hi:[1,0,1]
	v_pk_fma_f32 v[44:45], v[44:45], v[152:153], v[136:137] op_sel_hi:[1,0,1]
	v_mul_f32_e32 v40, v51, v40
	v_mul_f32_e32 v41, v43, v41
	v_mul_f32_e32 v43, 0xbfb8aa3b, v47
	v_mul_f32_e32 v40, v50, v40
	v_exp_f32_e32 v43, v43
	v_mul_f32_e32 v50, 0xbfb8aa3b, v45
	v_exp_f32_e32 v50, v50
	v_pk_fma_f32 v[48:49], v[48:49], v[152:153], v[126:127] op_sel_hi:[1,0,1]
	v_mul_f32_e32 v41, v42, v41
	v_add_f32_e32 v42, 1.0, v43
	v_rcp_f32_e32 v42, v42
	v_add_f32_e32 v43, 1.0, v50
	v_mul_f32_e32 v50, 0xbfb8aa3b, v49
	v_rcp_f32_e32 v43, v43
	v_exp_f32_e32 v50, v50
	v_pk_fma_f32 v[34:35], v[34:35], v[152:153], v[130:131] op_sel_hi:[1,0,1]
	v_mul_f32_e32 v42, v47, v42
	v_mul_f32_e32 v42, v46, v42
	v_mul_f32_e32 v43, v45, v43
	v_add_f32_e32 v45, 1.0, v50
	v_mul_f32_e32 v46, 0xbfb8aa3b, v35
	v_rcp_f32_e32 v45, v45
	v_exp_f32_e32 v46, v46
	v_pk_fma_f32 v[38:39], v[38:39], v[152:153], v[124:125] op_sel_hi:[1,0,1]
	v_pk_fma_f32 v[36:37], v[36:37], v[152:153], v[132:133] op_sel_hi:[1,0,1]
	v_mul_f32_e32 v43, v44, v43
	v_mul_f32_e32 v44, v49, v45
	v_add_f32_e32 v45, 1.0, v46
	v_mul_f32_e32 v46, 0xbfb8aa3b, v39
	v_rcp_f32_e32 v45, v45
	v_exp_f32_e32 v46, v46
	v_mul_f32_e32 v47, 0xbfb8aa3b, v37
	v_exp_f32_e32 v47, v47
	v_mul_f32_e32 v35, v35, v45
	v_add_f32_e32 v45, 1.0, v46
	v_rcp_f32_e32 v45, v45
	v_add_f32_e32 v46, 1.0, v47
	v_rcp_f32_e32 v46, v46
	v_mul_f32_e32 v47, v34, v35
	v_mul_f32_e32 v34, v39, v45
	v_mul_f32_e32 v38, v38, v34
	v_mul_f32_e32 v34, v37, v46
	v_mul_f32_e32 v37, v36, v34
	v_mul_f32_e32 v44, v48, v44
	v_cvt_pk_bf16_f32 v34, v40, v41
	v_cvt_pk_bf16_f32 v35, v42, v43
	v_cvt_pk_bf16_f32 v36, v44, v47
	v_cvt_pk_bf16_f32 v37, v38, v37
	v_mad_i64_i32 v[38:39], s[44:45], v161, s33, v[114:115]
	v_lshl_add_u64 v[38:39], v[38:39], 0, v[116:117]
	global_store_dwordx4 v[38:39], v[34:37], off
	s_nop 1
	v_mov_b32_e32 v34, v30
	v_mov_b32_e32 v35, v26
	v_pk_fma_f32 v[34:35], v[34:35], v[150:151], v[148:149] op_sel_hi:[1,0,1]
	v_mov_b32_e32 v26, v31
	v_pk_fma_f32 v[26:27], v[26:27], v[150:151], v[134:135] op_sel_hi:[1,0,1]
	v_mov_b32_e32 v31, v28
	v_mov_b32_e32 v28, v33
	v_mov_b32_e32 v33, v18
	v_mov_b32_e32 v18, v23
	v_mov_b32_e32 v23, v20
	v_mul_f32_e32 v20, 0xbfb8aa3b, v35
	v_mov_b32_e32 v30, v32
	v_mov_b32_e32 v32, v22
	v_mov_b32_e32 v22, v24
	v_exp_f32_e32 v24, v20
	v_mul_f32_e32 v20, 0xbfb8aa3b, v27
	v_exp_f32_e32 v36, v20
	v_mov_b32_e32 v20, v25
	v_add_f32_e32 v24, 1.0, v24
	v_rcp_f32_e32 v24, v24
	v_add_f32_e32 v25, 1.0, v36
	v_rcp_f32_e32 v25, v25
	v_pk_fma_f32 v[30:31], v[30:31], v[150:151], v[128:129] op_sel_hi:[1,0,1]
	v_pk_fma_f32 v[28:29], v[28:29], v[150:151], v[136:137] op_sel_hi:[1,0,1]
	v_mul_f32_e32 v24, v35, v24
	v_mul_f32_e32 v25, v27, v25
	v_mul_f32_e32 v27, 0xbfb8aa3b, v31
	v_mul_f32_e32 v24, v34, v24
	v_exp_f32_e32 v27, v27
	v_mul_f32_e32 v34, 0xbfb8aa3b, v29
	v_exp_f32_e32 v34, v34
	v_pk_fma_f32 v[32:33], v[32:33], v[150:151], v[126:127] op_sel_hi:[1,0,1]
	v_mul_f32_e32 v25, v26, v25
	v_add_f32_e32 v26, 1.0, v27
	v_rcp_f32_e32 v26, v26
	v_add_f32_e32 v27, 1.0, v34
	v_mul_f32_e32 v34, 0xbfb8aa3b, v33
	v_rcp_f32_e32 v27, v27
	v_exp_f32_e32 v34, v34
	v_pk_fma_f32 v[18:19], v[18:19], v[150:151], v[130:131] op_sel_hi:[1,0,1]
	v_mul_f32_e32 v26, v31, v26
	v_mul_f32_e32 v26, v30, v26
	v_mul_f32_e32 v27, v29, v27
	v_add_f32_e32 v29, 1.0, v34
	v_mul_f32_e32 v30, 0xbfb8aa3b, v19
	v_rcp_f32_e32 v29, v29
	v_exp_f32_e32 v30, v30
	v_pk_fma_f32 v[22:23], v[22:23], v[150:151], v[124:125] op_sel_hi:[1,0,1]
	v_pk_fma_f32 v[20:21], v[20:21], v[150:151], v[132:133] op_sel_hi:[1,0,1]
	v_mul_f32_e32 v27, v28, v27
	v_mul_f32_e32 v28, v33, v29
	v_add_f32_e32 v29, 1.0, v30
	v_mul_f32_e32 v30, 0xbfb8aa3b, v23
	v_rcp_f32_e32 v29, v29
	v_exp_f32_e32 v30, v30
	v_mul_f32_e32 v31, 0xbfb8aa3b, v21
	v_exp_f32_e32 v31, v31
	v_mul_f32_e32 v19, v19, v29
	v_add_f32_e32 v29, 1.0, v30
	v_rcp_f32_e32 v29, v29
	v_add_f32_e32 v30, 1.0, v31
	v_rcp_f32_e32 v30, v30
	v_mul_f32_e32 v31, v18, v19
	v_mul_f32_e32 v18, v23, v29
	v_mul_f32_e32 v22, v22, v18
	v_mul_f32_e32 v18, v21, v30
	v_mul_f32_e32 v21, v20, v18
	v_mul_f32_e32 v28, v32, v28
	v_cvt_pk_bf16_f32 v18, v24, v25
	v_cvt_pk_bf16_f32 v19, v26, v27
	v_cvt_pk_bf16_f32 v20, v28, v31
	v_cvt_pk_bf16_f32 v21, v22, v21
	v_mad_i64_i32 v[22:23], s[44:45], v160, s33, v[114:115]
	v_lshl_add_u64 v[22:23], v[22:23], 0, v[116:117]
	global_store_dwordx4 v[22:23], v[18:21], off
	s_nop 1
	v_mov_b32_e32 v18, v14
	v_mov_b32_e32 v19, v10
	v_pk_fma_f32 v[18:19], v[18:19], v[122:123], v[148:149] op_sel_hi:[1,0,1]
	v_mov_b32_e32 v10, v15
	v_mov_b32_e32 v15, v12
	v_mov_b32_e32 v12, v17
	v_mov_b32_e32 v17, v6
	v_mov_b32_e32 v6, v3
	v_pk_fma_f32 v[10:11], v[10:11], v[122:123], v[134:135] op_sel_hi:[1,0,1]
	v_mov_b32_e32 v14, v16
	v_mov_b32_e32 v16, v2
	v_pk_fma_f32 v[2:3], v[6:7], v[122:123], v[130:131] op_sel_hi:[1,0,1]
	v_mov_b32_e32 v6, v4
	v_mul_f32_e32 v4, 0xbfb8aa3b, v19
	v_mov_b32_e32 v7, v8
	v_exp_f32_e32 v4, v4
	v_mul_f32_e32 v8, 0xbfb8aa3b, v11
	v_exp_f32_e32 v20, v8
	v_pk_fma_f32 v[14:15], v[14:15], v[122:123], v[128:129] op_sel_hi:[1,0,1]
	v_add_f32_e32 v4, 1.0, v4
	v_rcp_f32_e32 v21, v4
	v_add_f32_e32 v4, 1.0, v20
	v_rcp_f32_e32 v20, v4
	v_mov_b32_e32 v8, v5
	v_pk_fma_f32 v[12:13], v[12:13], v[122:123], v[136:137] op_sel_hi:[1,0,1]
	v_pk_fma_f32 v[4:5], v[8:9], v[122:123], v[132:133] op_sel_hi:[1,0,1]
	v_mul_f32_e32 v8, v19, v21
	v_mul_f32_e32 v9, v11, v20
	v_mul_f32_e32 v11, 0xbfb8aa3b, v15
	v_mul_f32_e32 v8, v18, v8
	v_exp_f32_e32 v11, v11
	v_mul_f32_e32 v18, 0xbfb8aa3b, v13
	v_exp_f32_e32 v18, v18
	v_pk_fma_f32 v[16:17], v[16:17], v[122:123], v[126:127] op_sel_hi:[1,0,1]
	v_mul_f32_e32 v9, v10, v9
	v_add_f32_e32 v10, 1.0, v11
	v_rcp_f32_e32 v10, v10
	v_add_f32_e32 v11, 1.0, v18
	v_mul_f32_e32 v18, 0xbfb8aa3b, v17
	v_rcp_f32_e32 v11, v11
	v_exp_f32_e32 v18, v18
	v_mul_f32_e32 v10, v15, v10
	v_mul_f32_e32 v10, v14, v10
	v_mul_f32_e32 v11, v13, v11
	v_add_f32_e32 v13, 1.0, v18
	v_mul_f32_e32 v14, 0xbfb8aa3b, v3
	v_rcp_f32_e32 v13, v13
	v_exp_f32_e32 v14, v14
	v_pk_fma_f32 v[6:7], v[6:7], v[122:123], v[124:125] op_sel_hi:[1,0,1]
	v_mul_f32_e32 v11, v12, v11
	v_mul_f32_e32 v12, v17, v13
	v_add_f32_e32 v13, 1.0, v14
	v_mul_f32_e32 v14, 0xbfb8aa3b, v7
	v_rcp_f32_e32 v13, v13
	v_exp_f32_e32 v14, v14
	v_mul_f32_e32 v15, 0xbfb8aa3b, v5
	v_exp_f32_e32 v15, v15
	v_mul_f32_e32 v3, v3, v13
	v_add_f32_e32 v13, 1.0, v14
	v_rcp_f32_e32 v13, v13
	v_add_f32_e32 v14, 1.0, v15
	v_rcp_f32_e32 v14, v14
	v_mul_f32_e32 v15, v2, v3
	v_mul_f32_e32 v2, v7, v13
	v_mul_f32_e32 v6, v6, v2
	v_mul_f32_e32 v2, v5, v14
	v_mul_f32_e32 v5, v4, v2
	v_mul_f32_e32 v12, v16, v12
	v_cvt_pk_bf16_f32 v2, v8, v9
	v_cvt_pk_bf16_f32 v3, v10, v11
	v_cvt_pk_bf16_f32 v4, v12, v15
	v_cvt_pk_bf16_f32 v5, v6, v5
	v_mad_i64_i32 v[6:7], s[44:45], v123, s33, v[114:115]
	v_lshl_add_u64 v[6:7], v[6:7], 0, v[116:117]
	global_store_dwordx4 v[6:7], v[2:5], off
	s_cmp_eq_u32 s100, 0
	s_cbranch_scc1 .Lko_nog
	s_cmp_lg_u32 s62, 3
	s_cbranch_scc1 .Lko_nog
	s_cmp_lt_u32 s2, 0xa0
	s_cbranch_scc1 .Lko_nog
	v_writelane_b32 v255, s8, 1
	v_writelane_b32 v255, s9, 2
	v_writelane_b32 v255, s10, 3
	v_writelane_b32 v255, s11, 4
	v_writelane_b32 v255, s12, 5
	v_writelane_b32 v255, s13, 6
	v_writelane_b32 v255, s22, 7
	v_writelane_b32 v255, s24, 8
	v_writelane_b32 v255, s25, 9
	v_writelane_b32 v255, s26, 10
	v_writelane_b32 v255, s27, 11
	v_writelane_b32 v255, s28, 12
	v_writelane_b32 v255, s29, 13
	v_writelane_b32 v255, s30, 14
	v_writelane_b32 v255, s31, 15
	v_writelane_b32 v255, s36, 16
	v_writelane_b32 v255, s37, 17
	v_writelane_b32 v255, s38, 18
	v_writelane_b32 v255, s39, 19
	v_writelane_b32 v255, s40, 20
	v_writelane_b32 v255, s41, 21
	v_writelane_b32 v255, s42, 22
	v_writelane_b32 v255, s43, 23
	v_writelane_b32 v255, s52, 24
	v_writelane_b32 v255, s53, 25
	v_writelane_b32 v255, s70, 26
	v_writelane_b32 v255, s71, 27
	v_writelane_b32 v255, s74, 28
	v_writelane_b32 v255, s75, 29
	v_writelane_b32 v255, s76, 30
	v_writelane_b32 v255, s77, 31
	v_writelane_b32 v255, s78, 32
	v_writelane_b32 v255, s79, 33
	v_writelane_b32 v255, s82, 34
	v_writelane_b32 v255, s83, 35
	v_writelane_b32 v255, s84, 36
	v_writelane_b32 v255, s85, 37
	v_writelane_b32 v255, s90, 38
	v_writelane_b32 v255, s91, 39
	v_writelane_b32 v255, s92, 40
	v_writelane_b32 v255, s93, 41
	v_writelane_b32 v255, s94, 42
	v_writelane_b32 v255, s95, 43
	v_writelane_b32 v255, s96, 44
	v_writelane_b32 v255, s97, 45
	v_writelane_b32 v255, vcc_lo, 46
	v_writelane_b32 v255, vcc_hi, 47
	v_mov_b32_e32 v200, v0
	v_mov_b32_e32 v201, v2
	v_mov_b32_e32 v202, v3
	v_mov_b32_e32 v203, v4
	v_mov_b32_e32 v204, v5
	v_mov_b32_e32 v205, v6
	v_mov_b32_e32 v206, v7
	v_mov_b32_e32 v207, v8
	v_mov_b32_e32 v208, v9
	v_mov_b32_e32 v209, v10
	v_mov_b32_e32 v210, v11
	v_mov_b32_e32 v211, v12
	v_mov_b32_e32 v212, v13
	v_mov_b32_e32 v213, v14
	v_mov_b32_e32 v214, v15
	v_mov_b32_e32 v215, v16
	v_mov_b32_e32 v216, v17
	s_mov_b64 s[10:11], s[0:1]
	s_getreg_b32 s4, hwreg(HW_REG_XCC_ID, 0, 4)
	s_waitcnt vmcnt(0)
	s_waitcnt lgkmcnt(0)
	s_barrier
	s_and_saveexec_b64 s[8:9], s[78:79]
	s_cbranch_execz .Lko_g1440
	v_readlane_b32 s12, v253, 60
	s_load_dwordx2 s[10:11], s[10:11], 0xe0
	s_waitcnt vmcnt(0) expcnt(0) lgkmcnt(0)
	v_mov_b32_e32 v0, s12
	ds_read_b32 v3, v0
	v_readlane_b32 s12, v253, 61
	s_and_b32 s4, s4, 15
	s_waitcnt lgkmcnt(0)
	v_cmp_ne_u32_e32 vcc, 0, v3
	v_mov_b32_e32 v0, s12
	ds_read_b32 v2, v0
	s_cbranch_vccnz .Lko_g1404
	s_add_u32 s12, s10, 0x4200
	s_addc_u32 s13, s11, 0
	s_add_u32 s24, s10, 0x4400
	s_addc_u32 s25, s11, 0
	s_add_u32 s26, s10, 0x4500
	s_addc_u32 s27, s11, 0
	s_add_u32 s28, s10, 0x4600
	s_addc_u32 s29, s11, 0
	s_add_u32 s36, s10, 0x4700
	s_addc_u32 s37, s11, 0
	s_add_u32 s40, s10, 0x4800
	s_addc_u32 s41, s11, 0
	s_add_u32 s42, s10, 0x4900
	s_addc_u32 s43, s11, 0
	s_add_u32 s44, s10, 0x4a00
	s_addc_u32 s45, s11, 0
	s_add_u32 s48, s10, 0x4b00
	s_addc_u32 s49, s11, 0
	s_add_u32 s52, s10, 0x4c00
	s_addc_u32 s53, s11, 0
	s_add_u32 s70, s10, 0x4d00
	s_addc_u32 s71, s11, 0
	s_add_u32 s74, s10, 0x4e00
	s_addc_u32 s75, s11, 0
	s_add_u32 s76, s10, 0x4f00
	s_addc_u32 s77, s11, 0
	s_add_u32 s78, s10, 0x5000
	s_addc_u32 s79, s11, 0
	s_add_u32 s82, s10, 0x5100
	s_addc_u32 s83, s11, 0
	s_add_u32 s90, s10, 0x5200
	s_addc_u32 s91, s11, 0
	s_add_u32 s92, s10, 0x5300
	s_addc_u32 s93, s11, 0
	s_mov_b32 s22, 1
	s_branch .Lko_g1392

.Lko_g1440:
	s_or_b64 exec, exec, s[8:9]
	s_mov_b64 s[8:9], s[0:1]
	s_waitcnt lgkmcnt(0)
	s_barrier
	v_mov_b32_e32 v0, v200
	v_mov_b32_e32 v2, v201
	v_mov_b32_e32 v3, v202
	v_mov_b32_e32 v4, v203
	v_mov_b32_e32 v5, v204
	v_mov_b32_e32 v6, v205
	v_mov_b32_e32 v7, v206
	v_mov_b32_e32 v8, v207
	v_mov_b32_e32 v9, v208
	v_mov_b32_e32 v10, v209
	v_mov_b32_e32 v11, v210
	v_mov_b32_e32 v12, v211
	v_mov_b32_e32 v13, v212
	v_mov_b32_e32 v14, v213
	v_mov_b32_e32 v15, v214
	v_mov_b32_e32 v16, v215
	v_mov_b32_e32 v17, v216
	v_readlane_b32 s8, v255, 1
	v_readlane_b32 s9, v255, 2
	v_readlane_b32 s10, v255, 3
	v_readlane_b32 s11, v255, 4
	v_readlane_b32 s12, v255, 5
	v_readlane_b32 s13, v255, 6
	v_readlane_b32 s22, v255, 7
	v_readlane_b32 s24, v255, 8
	v_readlane_b32 s25, v255, 9
	v_readlane_b32 s26, v255, 10
	v_readlane_b32 s27, v255, 11
	v_readlane_b32 s28, v255, 12
	v_readlane_b32 s29, v255, 13
	v_readlane_b32 s30, v255, 14
	v_readlane_b32 s31, v255, 15
	v_readlane_b32 s36, v255, 16
	v_readlane_b32 s37, v255, 17
	v_readlane_b32 s38, v255, 18
	v_readlane_b32 s39, v255, 19
	v_readlane_b32 s40, v255, 20
	v_readlane_b32 s41, v255, 21
	v_readlane_b32 s42, v255, 22
	v_readlane_b32 s43, v255, 23
	v_readlane_b32 s52, v255, 24
	v_readlane_b32 s53, v255, 25
	v_readlane_b32 s70, v255, 26
	v_readlane_b32 s71, v255, 27
	v_readlane_b32 s74, v255, 28
	v_readlane_b32 s75, v255, 29
	v_readlane_b32 s76, v255, 30
	v_readlane_b32 s77, v255, 31
	v_readlane_b32 s78, v255, 32
	v_readlane_b32 s79, v255, 33
	v_readlane_b32 s82, v255, 34
	v_readlane_b32 s83, v255, 35
	v_readlane_b32 s84, v255, 36
	v_readlane_b32 s85, v255, 37
	v_readlane_b32 s90, v255, 38
	v_readlane_b32 s91, v255, 39
	v_readlane_b32 s92, v255, 40
	v_readlane_b32 s93, v255, 41
	v_readlane_b32 s94, v255, 42
	v_readlane_b32 s95, v255, 43
	v_readlane_b32 s96, v255, 44
	v_readlane_b32 s97, v255, 45
	v_readlane_b32 s44, v255, 46
	v_readlane_b32 s45, v255, 47
	s_nop 4
	s_mov_b64 vcc, s[44:45]
	s_nop 4
.Lko_nog:
	s_cmp_eq_u32 s100, 0
	s_cbranch_scc1 .Lko_nosig
	s_cmp_lt_u32 s62, 4
	s_cbranch_scc1 .Lko_nosig
	s_waitcnt vmcnt(0)
	s_barrier
	s_and_saveexec_b64 s[44:45], s[78:79]
	s_cbranch_execz .Lko_sigdone
	s_load_dwordx2 s[48:49], s[0:1], 0xe0
	buffer_wbl2 sc1
	s_lshl_b32 s4, s101, 6
	s_add_i32 s4, s4, s68
	s_lshl_b32 s4, s4, 2
	s_add_i32 s4, s4, 0x8000
	v_mov_b32_e32 v192, 0
	s_waitcnt vmcnt(0) lgkmcnt(0)
	s_add_u32 s48, s48, s4
	s_addc_u32 s49, s49, 0
	s_nop 4
	global_atomic_add v192, v252, s[48:49]
	s_waitcnt vmcnt(0)
.Lko_sigdone:
	s_or_b64 exec, exec, s[44:45]
.Lko_nosig:
	s_cbranch_vccnz .LBB0_1302
	s_andn2_b64 vcc, exec, s[24:25]
	s_cbranch_vccnz .LBB0_1301
	s_barrier
	s_branch .LBB0_1301

.LBB0_1387:
	s_mov_b64 s[10:11], s[0:1]
	s_getreg_b32 s4, hwreg(HW_REG_XCC_ID, 0, 4)
	s_cmp_eq_u32 s100, 0
	s_cbranch_scc1 .Lko_g1_do
	s_cmp_lt_u32 s2, 0xa0
	s_cbranch_scc0 .Lko_g1_skip
.Lko_g1_do:
	s_waitcnt vmcnt(0)
	s_waitcnt lgkmcnt(0)
	s_barrier
	s_and_saveexec_b64 s[8:9], s[78:79]
	s_cbranch_execz .LBB0_1440
	v_readlane_b32 s12, v253, 60
	s_load_dwordx2 s[10:11], s[10:11], 0xe0
	s_waitcnt vmcnt(0) expcnt(0) lgkmcnt(0)
	v_mov_b32_e32 v0, s12
	ds_read_b32 v3, v0
	v_readlane_b32 s12, v253, 61
	s_and_b32 s4, s4, 15
	s_waitcnt lgkmcnt(0)
	v_cmp_ne_u32_e32 vcc, 0, v3
	v_mov_b32_e32 v0, s12
	ds_read_b32 v2, v0
	s_cbranch_vccnz .LBB0_1404
	s_add_u32 s12, s10, 0x4200
	s_addc_u32 s13, s11, 0
	s_add_u32 s24, s10, 0x4400
	s_addc_u32 s25, s11, 0
	s_add_u32 s26, s10, 0x4500
	s_addc_u32 s27, s11, 0
	s_add_u32 s28, s10, 0x4600
	s_addc_u32 s29, s11, 0
	s_add_u32 s36, s10, 0x4700
	s_addc_u32 s37, s11, 0
	s_add_u32 s40, s10, 0x4800
	s_addc_u32 s41, s11, 0
	s_add_u32 s42, s10, 0x4900
	s_addc_u32 s43, s11, 0
	s_add_u32 s44, s10, 0x4a00
	s_addc_u32 s45, s11, 0
	s_add_u32 s48, s10, 0x4b00
	s_addc_u32 s49, s11, 0
	s_add_u32 s52, s10, 0x4c00
	s_addc_u32 s53, s11, 0
	s_add_u32 s70, s10, 0x4d00
	s_addc_u32 s71, s11, 0
	s_add_u32 s74, s10, 0x4e00
	s_addc_u32 s75, s11, 0
	s_add_u32 s76, s10, 0x4f00
	s_addc_u32 s77, s11, 0
	s_add_u32 s78, s10, 0x5000
	s_addc_u32 s79, s11, 0
	s_add_u32 s82, s10, 0x5100
	s_addc_u32 s83, s11, 0
	s_add_u32 s90, s10, 0x5200
	s_addc_u32 s91, s11, 0
	s_add_u32 s92, s10, 0x5300
	s_addc_u32 s93, s11, 0
	s_mov_b32 s22, 1
	s_branch .LBB0_1392

.Lko_g1_skip:
	s_mov_b64 s[8:9], s[0:1]
	s_waitcnt lgkmcnt(0)
	s_barrier
	s_load_dwordx2 s[48:49], s[8:9], 0xe0
	s_mov_b64 s[8:9], s[0:1]
	s_load_dwordx2 s[44:45], s[8:9], 0xe0
	v_readlane_b32 s8, v254, 34
	v_readlane_b32 s10, v254, 60
	v_readlane_b32 s9, v254, 35
	v_readlane_b32 s11, v254, 61
	s_and_b64 s[8:9], s[8:9], s[10:11]
	s_mov_b64 s[24:25], 0
	s_and_b64 vcc, exec, s[8:9]
	s_cbranch_vccnz .LBB0_1450
	s_mov_b64 s[10:11], -1
	s_and_b64 vcc, exec, s[14:15]
	s_cbranch_vccz .LBB0_1443
	s_mov_b64 s[8:9], s[0:1]
	s_mov_b64 s[10:11], 0

.LBB0_1474:
	s_cmp_lg_u32 s82, 36
	s_cbranch_scc1 .Lko_nopoll
	s_cmp_eq_u32 s100, 0
	s_cbranch_scc1 .Lko_nopoll
	s_load_dwordx2 s[90:91], s[0:1], 0xe0
	s_lshl_b32 s4, s101, 6
	s_add_i32 s4, s4, s84
	s_lshl_b32 s4, s4, 2
	s_add_i32 s4, s4, 0x8000
	s_cmp_lt_u32 s84, 8
	s_cselect_b32 s83, 2, 3
	s_waitcnt lgkmcnt(0)
	s_add_u32 s90, s90, s4
	s_addc_u32 s91, s91, 0
	s_mov_b32 s92, 0
	v_mov_b32_e32 v219, 0
	s_nop 4
.Lko_poll:
	global_load_dword v218, v219, s[90:91] sc1
	s_waitcnt vmcnt(0)
	v_readfirstlane_b32 s4, v218
	s_cmp_ge_u32 s4, s83
	s_cbranch_scc1 .Lko_nopoll
	s_sleep 4
	s_add_i32 s92, s92, 1
	s_cmp_lt_u32 s92, 0x2000
	s_cbranch_scc1 .Lko_poll
